# norm1 row loop: 4-row blocks, double-buffered loads (16-32 x 16B in flight per wave), interleaved butterfly reductions, saddr global loads/stores; same arithmetic order
# baseline (speedup 1.0000x reference)
.LBB0_67:
	s_or_b64 exec, exec, s[28:29]
	s_waitcnt lgkmcnt(0)
	s_barrier
	ds_read_b128 v[0:3], v34
	ds_read_b128 v[4:7], v34 offset:16
	ds_read_b128 v[8:11], v34 offset:4096
	ds_read_b128 v[12:15], v34 offset:4112
	ds_read_b128 v[60:63], v34 offset:2048
	ds_read_b128 v[64:67], v34 offset:2064
	ds_read_b128 v[68:71], v34 offset:6144
	ds_read_b128 v[72:75], v34 offset:6160
	v_readfirstlane_b32 s92, v26
	v_readfirstlane_b32 s93, v27
	v_readfirstlane_b32 s94, v24
	v_readfirstlane_b32 s95, v25
	v_lshrrev_b32_e32 v92, 1, v34
	s_mov_b32 s96, 3
	s_nop 4
	global_load_dwordx4 v[94:97], v34, s[92:93]
	global_load_dwordx4 v[98:101], v34, s[92:93] offset:16
	global_load_dwordx4 v[102:105], v34, s[92:93] offset:2048
	global_load_dwordx4 v[106:109], v34, s[92:93] offset:2064
	s_add_u32 s92, s92, 0x1000
	s_addc_u32 s93, s93, 0
	global_load_dwordx4 v[110:113], v34, s[92:93]
	global_load_dwordx4 v[114:117], v34, s[92:93] offset:16
	global_load_dwordx4 v[118:121], v34, s[92:93] offset:2048
	global_load_dwordx4 v[122:125], v34, s[92:93] offset:2064
	s_add_u32 s92, s92, 0x1000
	s_addc_u32 s93, s93, 0
	global_load_dwordx4 v[126:129], v34, s[92:93]
	global_load_dwordx4 v[130:133], v34, s[92:93] offset:16
	global_load_dwordx4 v[134:137], v34, s[92:93] offset:2048
	global_load_dwordx4 v[138:141], v34, s[92:93] offset:2064
	s_add_u32 s92, s92, 0x1000
	s_addc_u32 s93, s93, 0
	global_load_dwordx4 v[142:145], v34, s[92:93]
	global_load_dwordx4 v[146:149], v34, s[92:93] offset:16
	global_load_dwordx4 v[150:153], v34, s[92:93] offset:2048
	global_load_dwordx4 v[154:157], v34, s[92:93] offset:2064
	s_add_u32 s92, s92, 0x1000
	s_addc_u32 s93, s93, 0
	global_load_dwordx4 v[158:161], v34, s[92:93]
	global_load_dwordx4 v[162:165], v34, s[92:93] offset:16
	global_load_dwordx4 v[166:169], v34, s[92:93] offset:2048
	global_load_dwordx4 v[170:173], v34, s[92:93] offset:2064
	s_add_u32 s92, s92, 0x1000
	s_addc_u32 s93, s93, 0
	global_load_dwordx4 v[174:177], v34, s[92:93]
	global_load_dwordx4 v[178:181], v34, s[92:93] offset:16
	global_load_dwordx4 v[182:185], v34, s[92:93] offset:2048
	global_load_dwordx4 v[186:189], v34, s[92:93] offset:2064
	s_add_u32 s92, s92, 0x1000
	s_addc_u32 s93, s93, 0
	global_load_dwordx4 v[198:201], v34, s[92:93]
	global_load_dwordx4 v[202:205], v34, s[92:93] offset:16
	global_load_dwordx4 v[206:209], v34, s[92:93] offset:2048
	global_load_dwordx4 v[210:213], v34, s[92:93] offset:2064
	s_add_u32 s92, s92, 0x1000
	s_addc_u32 s93, s93, 0
	global_load_dwordx4 v[214:217], v34, s[92:93]
	global_load_dwordx4 v[218:221], v34, s[92:93] offset:16
	global_load_dwordx4 v[222:225], v34, s[92:93] offset:2048
	global_load_dwordx4 v[226:229], v34, s[92:93] offset:2064
	s_add_u32 s92, s92, 0x1000
	s_addc_u32 s93, s93, 0
	s_waitcnt vmcnt(16) lgkmcnt(0)
	v_mul_f32_e32 v48, v95, v95
	v_mul_f32_e32 v49, v99, v99
	v_mul_f32_e32 v50, v103, v103
	v_mul_f32_e32 v51, v107, v107
	v_fma_f32 v48, v94, v94, v48
	v_fma_f32 v49, v98, v98, v49
	v_fma_f32 v50, v102, v102, v50
	v_fma_f32 v51, v106, v106, v51
	v_fma_f32 v48, v96, v96, v48
	v_fma_f32 v49, v100, v100, v49
	v_fma_f32 v50, v104, v104, v50
	v_fma_f32 v51, v108, v108, v51
	v_fma_f32 v48, v97, v97, v48
	v_fma_f32 v49, v101, v101, v49
	v_fma_f32 v50, v105, v105, v50
	v_fma_f32 v51, v109, v109, v51
	v_add_f32_e32 v44, v48, v49
	v_add_f32_e32 v44, v44, v50
	v_add_f32_e32 v44, v44, v51
	v_mul_f32_e32 v56, v111, v111
	v_mul_f32_e32 v57, v115, v115
	v_mul_f32_e32 v58, v119, v119
	v_mul_f32_e32 v59, v123, v123
	v_fma_f32 v56, v110, v110, v56
	v_fma_f32 v57, v114, v114, v57
	v_fma_f32 v58, v118, v118, v58
	v_fma_f32 v59, v122, v122, v59
	v_fma_f32 v56, v112, v112, v56
	v_fma_f32 v57, v116, v116, v57
	v_fma_f32 v58, v120, v120, v58
	v_fma_f32 v59, v124, v124, v59
	v_fma_f32 v56, v113, v113, v56
	v_fma_f32 v57, v117, v117, v57
	v_fma_f32 v58, v121, v121, v58
	v_fma_f32 v59, v125, v125, v59
	v_add_f32_e32 v52, v56, v57
	v_add_f32_e32 v52, v52, v58
	v_add_f32_e32 v52, v52, v59
	v_mul_f32_e32 v80, v127, v127
	v_mul_f32_e32 v81, v131, v131
	v_mul_f32_e32 v82, v135, v135
	v_mul_f32_e32 v83, v139, v139
	v_fma_f32 v80, v126, v126, v80
	v_fma_f32 v81, v130, v130, v81
	v_fma_f32 v82, v134, v134, v82
	v_fma_f32 v83, v138, v138, v83
	v_fma_f32 v80, v128, v128, v80
	v_fma_f32 v81, v132, v132, v81
	v_fma_f32 v82, v136, v136, v82
	v_fma_f32 v83, v140, v140, v83
	v_fma_f32 v80, v129, v129, v80
	v_fma_f32 v81, v133, v133, v81
	v_fma_f32 v82, v137, v137, v82
	v_fma_f32 v83, v141, v141, v83
	v_add_f32_e32 v76, v80, v81
	v_add_f32_e32 v76, v76, v82
	v_add_f32_e32 v76, v76, v83
	v_mul_f32_e32 v88, v143, v143
	v_mul_f32_e32 v89, v147, v147
	v_mul_f32_e32 v90, v151, v151
	v_mul_f32_e32 v91, v155, v155
	v_fma_f32 v88, v142, v142, v88
	v_fma_f32 v89, v146, v146, v89
	v_fma_f32 v90, v150, v150, v90
	v_fma_f32 v91, v154, v154, v91
	v_fma_f32 v88, v144, v144, v88
	v_fma_f32 v89, v148, v148, v89
	v_fma_f32 v90, v152, v152, v90
	v_fma_f32 v91, v156, v156, v91
	v_fma_f32 v88, v145, v145, v88
	v_fma_f32 v89, v149, v149, v89
	v_fma_f32 v90, v153, v153, v90
	v_fma_f32 v91, v157, v157, v91
	v_add_f32_e32 v84, v88, v89
	v_add_f32_e32 v84, v84, v90
	v_add_f32_e32 v84, v84, v91
	ds_bpermute_b32 v45, v35, v44
	ds_bpermute_b32 v53, v35, v52
	ds_bpermute_b32 v77, v35, v76
	ds_bpermute_b32 v85, v35, v84
	s_waitcnt lgkmcnt(0)
	v_add_f32_e32 v44, v44, v45
	v_add_f32_e32 v52, v52, v53
	v_add_f32_e32 v76, v76, v77
	v_add_f32_e32 v84, v84, v85
	ds_bpermute_b32 v45, v36, v44
	ds_bpermute_b32 v53, v36, v52
	ds_bpermute_b32 v77, v36, v76
	ds_bpermute_b32 v85, v36, v84
	s_waitcnt lgkmcnt(0)
	v_add_f32_e32 v44, v44, v45
	v_add_f32_e32 v52, v52, v53
	v_add_f32_e32 v76, v76, v77
	v_add_f32_e32 v84, v84, v85
	ds_bpermute_b32 v45, v37, v44
	ds_bpermute_b32 v53, v37, v52
	ds_bpermute_b32 v77, v37, v76
	ds_bpermute_b32 v85, v37, v84
	s_waitcnt lgkmcnt(0)
	v_add_f32_e32 v44, v44, v45
	v_add_f32_e32 v52, v52, v53
	v_add_f32_e32 v76, v76, v77
	v_add_f32_e32 v84, v84, v85
	ds_bpermute_b32 v45, v38, v44
	ds_bpermute_b32 v53, v38, v52
	ds_bpermute_b32 v77, v38, v76
	ds_bpermute_b32 v85, v38, v84
	s_waitcnt lgkmcnt(0)
	v_add_f32_e32 v44, v44, v45
	v_add_f32_e32 v52, v52, v53
	v_add_f32_e32 v76, v76, v77
	v_add_f32_e32 v84, v84, v85
	ds_bpermute_b32 v45, v39, v44
	ds_bpermute_b32 v53, v39, v52
	ds_bpermute_b32 v77, v39, v76
	ds_bpermute_b32 v85, v39, v84
	s_waitcnt lgkmcnt(0)
	v_add_f32_e32 v44, v44, v45
	v_add_f32_e32 v52, v52, v53
	v_add_f32_e32 v76, v76, v77
	v_add_f32_e32 v84, v84, v85
	ds_bpermute_b32 v45, v40, v44
	ds_bpermute_b32 v53, v40, v52
	ds_bpermute_b32 v77, v40, v76
	ds_bpermute_b32 v85, v40, v84
	s_waitcnt lgkmcnt(0)
	v_add_f32_e32 v44, v44, v45
	v_add_f32_e32 v52, v52, v53
	v_add_f32_e32 v76, v76, v77
	v_add_f32_e32 v84, v84, v85
	v_fmamk_f32 v44, v44, 0x3a800000, v42
	v_mul_f32_e32 v45, 0x4b800000, v44
	v_cmp_gt_f32_e32 vcc, s46, v44
	s_nop 1
	v_cndmask_b32_e32 v44, v44, v45, vcc
	v_rsq_f32_e32 v44, v44
	s_nop 0
	v_mul_f32_e32 v45, 0x45800000, v44
	v_cndmask_b32_e32 v46, v44, v45, vcc
	v_fmamk_f32 v52, v52, 0x3a800000, v42
	v_mul_f32_e32 v53, 0x4b800000, v52
	v_cmp_gt_f32_e32 vcc, s46, v52
	s_nop 1
	v_cndmask_b32_e32 v52, v52, v53, vcc
	v_rsq_f32_e32 v52, v52
	s_nop 0
	v_mul_f32_e32 v53, 0x45800000, v52
	v_cndmask_b32_e32 v54, v52, v53, vcc
	v_fmamk_f32 v76, v76, 0x3a800000, v42
	v_mul_f32_e32 v77, 0x4b800000, v76
	v_cmp_gt_f32_e32 vcc, s46, v76
	s_nop 1
	v_cndmask_b32_e32 v76, v76, v77, vcc
	v_rsq_f32_e32 v76, v76
	s_nop 0
	v_mul_f32_e32 v77, 0x45800000, v76
	v_cndmask_b32_e32 v78, v76, v77, vcc
	v_fmamk_f32 v84, v84, 0x3a800000, v42
	v_mul_f32_e32 v85, 0x4b800000, v84
	v_cmp_gt_f32_e32 vcc, s46, v84
	s_nop 1
	v_cndmask_b32_e32 v84, v84, v85, vcc
	v_rsq_f32_e32 v84, v84
	s_nop 0
	v_mul_f32_e32 v85, 0x45800000, v84
	v_cndmask_b32_e32 v86, v84, v85, vcc
	v_pk_mul_f32 v[94:95], v[94:95], v[46:47] op_sel_hi:[1,0]
	v_pk_mul_f32 v[96:97], v[96:97], v[46:47] op_sel_hi:[1,0]
	v_pk_mul_f32 v[98:99], v[98:99], v[46:47] op_sel_hi:[1,0]
	v_pk_mul_f32 v[100:101], v[100:101], v[46:47] op_sel_hi:[1,0]
	v_pk_mul_f32 v[102:103], v[102:103], v[46:47] op_sel_hi:[1,0]
	v_pk_mul_f32 v[104:105], v[104:105], v[46:47] op_sel_hi:[1,0]
	v_pk_mul_f32 v[106:107], v[106:107], v[46:47] op_sel_hi:[1,0]
	v_pk_mul_f32 v[108:109], v[108:109], v[46:47] op_sel_hi:[1,0]
	v_pk_fma_f32 v[94:95], v[0:1], v[94:95], v[8:9]
	v_pk_fma_f32 v[96:97], v[2:3], v[96:97], v[10:11]
	v_pk_fma_f32 v[98:99], v[4:5], v[98:99], v[12:13]
	v_pk_fma_f32 v[100:101], v[6:7], v[100:101], v[14:15]
	v_pk_fma_f32 v[102:103], v[60:61], v[102:103], v[68:69]
	v_pk_fma_f32 v[104:105], v[62:63], v[104:105], v[70:71]
	v_pk_fma_f32 v[106:107], v[64:65], v[106:107], v[72:73]
	v_pk_fma_f32 v[108:109], v[66:67], v[108:109], v[74:75]
	v_cvt_pk_bf16_f32 v94, v94, v95
	v_cvt_pk_bf16_f32 v95, v96, v97
	v_cvt_pk_bf16_f32 v96, v98, v99
	v_cvt_pk_bf16_f32 v97, v100, v101
	v_cvt_pk_bf16_f32 v98, v102, v103
	v_cvt_pk_bf16_f32 v99, v104, v105
	v_cvt_pk_bf16_f32 v100, v106, v107
	v_cvt_pk_bf16_f32 v101, v108, v109
	v_pk_mul_f32 v[110:111], v[110:111], v[54:55] op_sel_hi:[1,0]
	v_pk_mul_f32 v[112:113], v[112:113], v[54:55] op_sel_hi:[1,0]
	v_pk_mul_f32 v[114:115], v[114:115], v[54:55] op_sel_hi:[1,0]
	v_pk_mul_f32 v[116:117], v[116:117], v[54:55] op_sel_hi:[1,0]
	v_pk_mul_f32 v[118:119], v[118:119], v[54:55] op_sel_hi:[1,0]
	v_pk_mul_f32 v[120:121], v[120:121], v[54:55] op_sel_hi:[1,0]
	v_pk_mul_f32 v[122:123], v[122:123], v[54:55] op_sel_hi:[1,0]
	v_pk_mul_f32 v[124:125], v[124:125], v[54:55] op_sel_hi:[1,0]
	v_pk_fma_f32 v[110:111], v[0:1], v[110:111], v[8:9]
	v_pk_fma_f32 v[112:113], v[2:3], v[112:113], v[10:11]
	v_pk_fma_f32 v[114:115], v[4:5], v[114:115], v[12:13]
	v_pk_fma_f32 v[116:117], v[6:7], v[116:117], v[14:15]
	v_pk_fma_f32 v[118:119], v[60:61], v[118:119], v[68:69]
	v_pk_fma_f32 v[120:121], v[62:63], v[120:121], v[70:71]
	v_pk_fma_f32 v[122:123], v[64:65], v[122:123], v[72:73]
	v_pk_fma_f32 v[124:125], v[66:67], v[124:125], v[74:75]
	v_cvt_pk_bf16_f32 v110, v110, v111
	v_cvt_pk_bf16_f32 v111, v112, v113
	v_cvt_pk_bf16_f32 v112, v114, v115
	v_cvt_pk_bf16_f32 v113, v116, v117
	v_cvt_pk_bf16_f32 v114, v118, v119
	v_cvt_pk_bf16_f32 v115, v120, v121
	v_cvt_pk_bf16_f32 v116, v122, v123
	v_cvt_pk_bf16_f32 v117, v124, v125
	v_pk_mul_f32 v[126:127], v[126:127], v[78:79] op_sel_hi:[1,0]
	v_pk_mul_f32 v[128:129], v[128:129], v[78:79] op_sel_hi:[1,0]
	v_pk_mul_f32 v[130:131], v[130:131], v[78:79] op_sel_hi:[1,0]
	v_pk_mul_f32 v[132:133], v[132:133], v[78:79] op_sel_hi:[1,0]
	v_pk_mul_f32 v[134:135], v[134:135], v[78:79] op_sel_hi:[1,0]
	v_pk_mul_f32 v[136:137], v[136:137], v[78:79] op_sel_hi:[1,0]
	v_pk_mul_f32 v[138:139], v[138:139], v[78:79] op_sel_hi:[1,0]
	v_pk_mul_f32 v[140:141], v[140:141], v[78:79] op_sel_hi:[1,0]
	v_pk_fma_f32 v[126:127], v[0:1], v[126:127], v[8:9]
	v_pk_fma_f32 v[128:129], v[2:3], v[128:129], v[10:11]
	v_pk_fma_f32 v[130:131], v[4:5], v[130:131], v[12:13]
	v_pk_fma_f32 v[132:133], v[6:7], v[132:133], v[14:15]
	v_pk_fma_f32 v[134:135], v[60:61], v[134:135], v[68:69]
	v_pk_fma_f32 v[136:137], v[62:63], v[136:137], v[70:71]
	v_pk_fma_f32 v[138:139], v[64:65], v[138:139], v[72:73]
	v_pk_fma_f32 v[140:141], v[66:67], v[140:141], v[74:75]
	v_cvt_pk_bf16_f32 v126, v126, v127
	v_cvt_pk_bf16_f32 v127, v128, v129
	v_cvt_pk_bf16_f32 v128, v130, v131
	v_cvt_pk_bf16_f32 v129, v132, v133
	v_cvt_pk_bf16_f32 v130, v134, v135
	v_cvt_pk_bf16_f32 v131, v136, v137
	v_cvt_pk_bf16_f32 v132, v138, v139
	v_cvt_pk_bf16_f32 v133, v140, v141
	v_pk_mul_f32 v[142:143], v[142:143], v[86:87] op_sel_hi:[1,0]
	v_pk_mul_f32 v[144:145], v[144:145], v[86:87] op_sel_hi:[1,0]
	v_pk_mul_f32 v[146:147], v[146:147], v[86:87] op_sel_hi:[1,0]
	v_pk_mul_f32 v[148:149], v[148:149], v[86:87] op_sel_hi:[1,0]
	v_pk_mul_f32 v[150:151], v[150:151], v[86:87] op_sel_hi:[1,0]
	v_pk_mul_f32 v[152:153], v[152:153], v[86:87] op_sel_hi:[1,0]
	v_pk_mul_f32 v[154:155], v[154:155], v[86:87] op_sel_hi:[1,0]
	v_pk_mul_f32 v[156:157], v[156:157], v[86:87] op_sel_hi:[1,0]
	v_pk_fma_f32 v[142:143], v[0:1], v[142:143], v[8:9]
	v_pk_fma_f32 v[144:145], v[2:3], v[144:145], v[10:11]
	v_pk_fma_f32 v[146:147], v[4:5], v[146:147], v[12:13]
	v_pk_fma_f32 v[148:149], v[6:7], v[148:149], v[14:15]
	v_pk_fma_f32 v[150:151], v[60:61], v[150:151], v[68:69]
	v_pk_fma_f32 v[152:153], v[62:63], v[152:153], v[70:71]
	v_pk_fma_f32 v[154:155], v[64:65], v[154:155], v[72:73]
	v_pk_fma_f32 v[156:157], v[66:67], v[156:157], v[74:75]
	v_cvt_pk_bf16_f32 v142, v142, v143
	v_cvt_pk_bf16_f32 v143, v144, v145
	v_cvt_pk_bf16_f32 v144, v146, v147
	v_cvt_pk_bf16_f32 v145, v148, v149
	v_cvt_pk_bf16_f32 v146, v150, v151
	v_cvt_pk_bf16_f32 v147, v152, v153
	v_cvt_pk_bf16_f32 v148, v154, v155
	v_cvt_pk_bf16_f32 v149, v156, v157
	global_store_dwordx4 v92, v[94:97], s[94:95] offset:0
	global_store_dwordx4 v92, v[98:101], s[94:95] offset:1024
	global_store_dwordx4 v92, v[110:113], s[94:95] offset:2048
	global_store_dwordx4 v92, v[114:117], s[94:95] offset:3072
	s_add_u32 s94, s94, 0x1000
	s_addc_u32 s95, s95, 0
	global_store_dwordx4 v92, v[126:129], s[94:95] offset:0
	global_store_dwordx4 v92, v[130:133], s[94:95] offset:1024
	global_store_dwordx4 v92, v[142:145], s[94:95] offset:2048
	global_store_dwordx4 v92, v[146:149], s[94:95] offset:3072
	s_add_u32 s94, s94, 0x1000
	s_addc_u32 s95, s95, 0
.Ln1_loop:
	global_load_dwordx4 v[94:97], v34, s[92:93]
	global_load_dwordx4 v[98:101], v34, s[92:93] offset:16
	global_load_dwordx4 v[102:105], v34, s[92:93] offset:2048
	global_load_dwordx4 v[106:109], v34, s[92:93] offset:2064
	s_add_u32 s92, s92, 0x1000
	s_addc_u32 s93, s93, 0
	global_load_dwordx4 v[110:113], v34, s[92:93]
	global_load_dwordx4 v[114:117], v34, s[92:93] offset:16
	global_load_dwordx4 v[118:121], v34, s[92:93] offset:2048
	global_load_dwordx4 v[122:125], v34, s[92:93] offset:2064
	s_add_u32 s92, s92, 0x1000
	s_addc_u32 s93, s93, 0
	global_load_dwordx4 v[126:129], v34, s[92:93]
	global_load_dwordx4 v[130:133], v34, s[92:93] offset:16
	global_load_dwordx4 v[134:137], v34, s[92:93] offset:2048
	global_load_dwordx4 v[138:141], v34, s[92:93] offset:2064
	s_add_u32 s92, s92, 0x1000
	s_addc_u32 s93, s93, 0
	global_load_dwordx4 v[142:145], v34, s[92:93]
	global_load_dwordx4 v[146:149], v34, s[92:93] offset:16
	global_load_dwordx4 v[150:153], v34, s[92:93] offset:2048
	global_load_dwordx4 v[154:157], v34, s[92:93] offset:2064
	s_add_u32 s92, s92, 0x1000
	s_addc_u32 s93, s93, 0
	s_waitcnt vmcnt(24)
	v_mul_f32_e32 v48, v159, v159
	v_mul_f32_e32 v49, v163, v163
	v_mul_f32_e32 v50, v167, v167
	v_mul_f32_e32 v51, v171, v171
	v_fma_f32 v48, v158, v158, v48
	v_fma_f32 v49, v162, v162, v49
	v_fma_f32 v50, v166, v166, v50
	v_fma_f32 v51, v170, v170, v51
	v_fma_f32 v48, v160, v160, v48
	v_fma_f32 v49, v164, v164, v49
	v_fma_f32 v50, v168, v168, v50
	v_fma_f32 v51, v172, v172, v51
	v_fma_f32 v48, v161, v161, v48
	v_fma_f32 v49, v165, v165, v49
	v_fma_f32 v50, v169, v169, v50
	v_fma_f32 v51, v173, v173, v51
	v_add_f32_e32 v44, v48, v49
	v_add_f32_e32 v44, v44, v50
	v_add_f32_e32 v44, v44, v51
	v_mul_f32_e32 v56, v175, v175
	v_mul_f32_e32 v57, v179, v179
	v_mul_f32_e32 v58, v183, v183
	v_mul_f32_e32 v59, v187, v187
	v_fma_f32 v56, v174, v174, v56
	v_fma_f32 v57, v178, v178, v57
	v_fma_f32 v58, v182, v182, v58
	v_fma_f32 v59, v186, v186, v59
	v_fma_f32 v56, v176, v176, v56
	v_fma_f32 v57, v180, v180, v57
	v_fma_f32 v58, v184, v184, v58
	v_fma_f32 v59, v188, v188, v59
	v_fma_f32 v56, v177, v177, v56
	v_fma_f32 v57, v181, v181, v57
	v_fma_f32 v58, v185, v185, v58
	v_fma_f32 v59, v189, v189, v59
	v_add_f32_e32 v52, v56, v57
	v_add_f32_e32 v52, v52, v58
	v_add_f32_e32 v52, v52, v59
	v_mul_f32_e32 v80, v199, v199
	v_mul_f32_e32 v81, v203, v203
	v_mul_f32_e32 v82, v207, v207
	v_mul_f32_e32 v83, v211, v211
	v_fma_f32 v80, v198, v198, v80
	v_fma_f32 v81, v202, v202, v81
	v_fma_f32 v82, v206, v206, v82
	v_fma_f32 v83, v210, v210, v83
	v_fma_f32 v80, v200, v200, v80
	v_fma_f32 v81, v204, v204, v81
	v_fma_f32 v82, v208, v208, v82
	v_fma_f32 v83, v212, v212, v83
	v_fma_f32 v80, v201, v201, v80
	v_fma_f32 v81, v205, v205, v81
	v_fma_f32 v82, v209, v209, v82
	v_fma_f32 v83, v213, v213, v83
	v_add_f32_e32 v76, v80, v81
	v_add_f32_e32 v76, v76, v82
	v_add_f32_e32 v76, v76, v83
	v_mul_f32_e32 v88, v215, v215
	v_mul_f32_e32 v89, v219, v219
	v_mul_f32_e32 v90, v223, v223
	v_mul_f32_e32 v91, v227, v227
	v_fma_f32 v88, v214, v214, v88
	v_fma_f32 v89, v218, v218, v89
	v_fma_f32 v90, v222, v222, v90
	v_fma_f32 v91, v226, v226, v91
	v_fma_f32 v88, v216, v216, v88
	v_fma_f32 v89, v220, v220, v89
	v_fma_f32 v90, v224, v224, v90
	v_fma_f32 v91, v228, v228, v91
	v_fma_f32 v88, v217, v217, v88
	v_fma_f32 v89, v221, v221, v89
	v_fma_f32 v90, v225, v225, v90
	v_fma_f32 v91, v229, v229, v91
	v_add_f32_e32 v84, v88, v89
	v_add_f32_e32 v84, v84, v90
	v_add_f32_e32 v84, v84, v91
	ds_bpermute_b32 v45, v35, v44
	ds_bpermute_b32 v53, v35, v52
	ds_bpermute_b32 v77, v35, v76
	ds_bpermute_b32 v85, v35, v84
	s_waitcnt lgkmcnt(0)
	v_add_f32_e32 v44, v44, v45
	v_add_f32_e32 v52, v52, v53
	v_add_f32_e32 v76, v76, v77
	v_add_f32_e32 v84, v84, v85
	ds_bpermute_b32 v45, v36, v44
	ds_bpermute_b32 v53, v36, v52
	ds_bpermute_b32 v77, v36, v76
	ds_bpermute_b32 v85, v36, v84
	s_waitcnt lgkmcnt(0)
	v_add_f32_e32 v44, v44, v45
	v_add_f32_e32 v52, v52, v53
	v_add_f32_e32 v76, v76, v77
	v_add_f32_e32 v84, v84, v85
	ds_bpermute_b32 v45, v37, v44
	ds_bpermute_b32 v53, v37, v52
	ds_bpermute_b32 v77, v37, v76
	ds_bpermute_b32 v85, v37, v84
	s_waitcnt lgkmcnt(0)
	v_add_f32_e32 v44, v44, v45
	v_add_f32_e32 v52, v52, v53
	v_add_f32_e32 v76, v76, v77
	v_add_f32_e32 v84, v84, v85
	ds_bpermute_b32 v45, v38, v44
	ds_bpermute_b32 v53, v38, v52
	ds_bpermute_b32 v77, v38, v76
	ds_bpermute_b32 v85, v38, v84
	s_waitcnt lgkmcnt(0)
	v_add_f32_e32 v44, v44, v45
	v_add_f32_e32 v52, v52, v53
	v_add_f32_e32 v76, v76, v77
	v_add_f32_e32 v84, v84, v85
	ds_bpermute_b32 v45, v39, v44
	ds_bpermute_b32 v53, v39, v52
	ds_bpermute_b32 v77, v39, v76
	ds_bpermute_b32 v85, v39, v84
	s_waitcnt lgkmcnt(0)
	v_add_f32_e32 v44, v44, v45
	v_add_f32_e32 v52, v52, v53
	v_add_f32_e32 v76, v76, v77
	v_add_f32_e32 v84, v84, v85
	ds_bpermute_b32 v45, v40, v44
	ds_bpermute_b32 v53, v40, v52
	ds_bpermute_b32 v77, v40, v76
	ds_bpermute_b32 v85, v40, v84
	s_waitcnt lgkmcnt(0)
	v_add_f32_e32 v44, v44, v45
	v_add_f32_e32 v52, v52, v53
	v_add_f32_e32 v76, v76, v77
	v_add_f32_e32 v84, v84, v85
	v_fmamk_f32 v44, v44, 0x3a800000, v42
	v_mul_f32_e32 v45, 0x4b800000, v44
	v_cmp_gt_f32_e32 vcc, s46, v44
	s_nop 1
	v_cndmask_b32_e32 v44, v44, v45, vcc
	v_rsq_f32_e32 v44, v44
	s_nop 0
	v_mul_f32_e32 v45, 0x45800000, v44
	v_cndmask_b32_e32 v46, v44, v45, vcc
	v_fmamk_f32 v52, v52, 0x3a800000, v42
	v_mul_f32_e32 v53, 0x4b800000, v52
	v_cmp_gt_f32_e32 vcc, s46, v52
	s_nop 1
	v_cndmask_b32_e32 v52, v52, v53, vcc
	v_rsq_f32_e32 v52, v52
	s_nop 0
	v_mul_f32_e32 v53, 0x45800000, v52
	v_cndmask_b32_e32 v54, v52, v53, vcc
	v_fmamk_f32 v76, v76, 0x3a800000, v42
	v_mul_f32_e32 v77, 0x4b800000, v76
	v_cmp_gt_f32_e32 vcc, s46, v76
	s_nop 1
	v_cndmask_b32_e32 v76, v76, v77, vcc
	v_rsq_f32_e32 v76, v76
	s_nop 0
	v_mul_f32_e32 v77, 0x45800000, v76
	v_cndmask_b32_e32 v78, v76, v77, vcc
	v_fmamk_f32 v84, v84, 0x3a800000, v42
	v_mul_f32_e32 v85, 0x4b800000, v84
	v_cmp_gt_f32_e32 vcc, s46, v84
	s_nop 1
	v_cndmask_b32_e32 v84, v84, v85, vcc
	v_rsq_f32_e32 v84, v84
	s_nop 0
	v_mul_f32_e32 v85, 0x45800000, v84
	v_cndmask_b32_e32 v86, v84, v85, vcc
	v_pk_mul_f32 v[158:159], v[158:159], v[46:47] op_sel_hi:[1,0]
	v_pk_mul_f32 v[160:161], v[160:161], v[46:47] op_sel_hi:[1,0]
	v_pk_mul_f32 v[162:163], v[162:163], v[46:47] op_sel_hi:[1,0]
	v_pk_mul_f32 v[164:165], v[164:165], v[46:47] op_sel_hi:[1,0]
	v_pk_mul_f32 v[166:167], v[166:167], v[46:47] op_sel_hi:[1,0]
	v_pk_mul_f32 v[168:169], v[168:169], v[46:47] op_sel_hi:[1,0]
	v_pk_mul_f32 v[170:171], v[170:171], v[46:47] op_sel_hi:[1,0]
	v_pk_mul_f32 v[172:173], v[172:173], v[46:47] op_sel_hi:[1,0]
	v_pk_fma_f32 v[158:159], v[0:1], v[158:159], v[8:9]
	v_pk_fma_f32 v[160:161], v[2:3], v[160:161], v[10:11]
	v_pk_fma_f32 v[162:163], v[4:5], v[162:163], v[12:13]
	v_pk_fma_f32 v[164:165], v[6:7], v[164:165], v[14:15]
	v_pk_fma_f32 v[166:167], v[60:61], v[166:167], v[68:69]
	v_pk_fma_f32 v[168:169], v[62:63], v[168:169], v[70:71]
	v_pk_fma_f32 v[170:171], v[64:65], v[170:171], v[72:73]
	v_pk_fma_f32 v[172:173], v[66:67], v[172:173], v[74:75]
	v_cvt_pk_bf16_f32 v158, v158, v159
	v_cvt_pk_bf16_f32 v159, v160, v161
	v_cvt_pk_bf16_f32 v160, v162, v163
	v_cvt_pk_bf16_f32 v161, v164, v165
	v_cvt_pk_bf16_f32 v162, v166, v167
	v_cvt_pk_bf16_f32 v163, v168, v169
	v_cvt_pk_bf16_f32 v164, v170, v171
	v_cvt_pk_bf16_f32 v165, v172, v173
	v_pk_mul_f32 v[174:175], v[174:175], v[54:55] op_sel_hi:[1,0]
	v_pk_mul_f32 v[176:177], v[176:177], v[54:55] op_sel_hi:[1,0]
	v_pk_mul_f32 v[178:179], v[178:179], v[54:55] op_sel_hi:[1,0]
	v_pk_mul_f32 v[180:181], v[180:181], v[54:55] op_sel_hi:[1,0]
	v_pk_mul_f32 v[182:183], v[182:183], v[54:55] op_sel_hi:[1,0]
	v_pk_mul_f32 v[184:185], v[184:185], v[54:55] op_sel_hi:[1,0]
	v_pk_mul_f32 v[186:187], v[186:187], v[54:55] op_sel_hi:[1,0]
	v_pk_mul_f32 v[188:189], v[188:189], v[54:55] op_sel_hi:[1,0]
	v_pk_fma_f32 v[174:175], v[0:1], v[174:175], v[8:9]
	v_pk_fma_f32 v[176:177], v[2:3], v[176:177], v[10:11]
	v_pk_fma_f32 v[178:179], v[4:5], v[178:179], v[12:13]
	v_pk_fma_f32 v[180:181], v[6:7], v[180:181], v[14:15]
	v_pk_fma_f32 v[182:183], v[60:61], v[182:183], v[68:69]
	v_pk_fma_f32 v[184:185], v[62:63], v[184:185], v[70:71]
	v_pk_fma_f32 v[186:187], v[64:65], v[186:187], v[72:73]
	v_pk_fma_f32 v[188:189], v[66:67], v[188:189], v[74:75]
	v_cvt_pk_bf16_f32 v174, v174, v175
	v_cvt_pk_bf16_f32 v175, v176, v177
	v_cvt_pk_bf16_f32 v176, v178, v179
	v_cvt_pk_bf16_f32 v177, v180, v181
	v_cvt_pk_bf16_f32 v178, v182, v183
	v_cvt_pk_bf16_f32 v179, v184, v185
	v_cvt_pk_bf16_f32 v180, v186, v187
	v_cvt_pk_bf16_f32 v181, v188, v189
	v_pk_mul_f32 v[198:199], v[198:199], v[78:79] op_sel_hi:[1,0]
	v_pk_mul_f32 v[200:201], v[200:201], v[78:79] op_sel_hi:[1,0]
	v_pk_mul_f32 v[202:203], v[202:203], v[78:79] op_sel_hi:[1,0]
	v_pk_mul_f32 v[204:205], v[204:205], v[78:79] op_sel_hi:[1,0]
	v_pk_mul_f32 v[206:207], v[206:207], v[78:79] op_sel_hi:[1,0]
	v_pk_mul_f32 v[208:209], v[208:209], v[78:79] op_sel_hi:[1,0]
	v_pk_mul_f32 v[210:211], v[210:211], v[78:79] op_sel_hi:[1,0]
	v_pk_mul_f32 v[212:213], v[212:213], v[78:79] op_sel_hi:[1,0]
	v_pk_fma_f32 v[198:199], v[0:1], v[198:199], v[8:9]
	v_pk_fma_f32 v[200:201], v[2:3], v[200:201], v[10:11]
	v_pk_fma_f32 v[202:203], v[4:5], v[202:203], v[12:13]
	v_pk_fma_f32 v[204:205], v[6:7], v[204:205], v[14:15]
	v_pk_fma_f32 v[206:207], v[60:61], v[206:207], v[68:69]
	v_pk_fma_f32 v[208:209], v[62:63], v[208:209], v[70:71]
	v_pk_fma_f32 v[210:211], v[64:65], v[210:211], v[72:73]
	v_pk_fma_f32 v[212:213], v[66:67], v[212:213], v[74:75]
	v_cvt_pk_bf16_f32 v198, v198, v199
	v_cvt_pk_bf16_f32 v199, v200, v201
	v_cvt_pk_bf16_f32 v200, v202, v203
	v_cvt_pk_bf16_f32 v201, v204, v205
	v_cvt_pk_bf16_f32 v202, v206, v207
	v_cvt_pk_bf16_f32 v203, v208, v209
	v_cvt_pk_bf16_f32 v204, v210, v211
	v_cvt_pk_bf16_f32 v205, v212, v213
	v_pk_mul_f32 v[214:215], v[214:215], v[86:87] op_sel_hi:[1,0]
	v_pk_mul_f32 v[216:217], v[216:217], v[86:87] op_sel_hi:[1,0]
	v_pk_mul_f32 v[218:219], v[218:219], v[86:87] op_sel_hi:[1,0]
	v_pk_mul_f32 v[220:221], v[220:221], v[86:87] op_sel_hi:[1,0]
	v_pk_mul_f32 v[222:223], v[222:223], v[86:87] op_sel_hi:[1,0]
	v_pk_mul_f32 v[224:225], v[224:225], v[86:87] op_sel_hi:[1,0]
	v_pk_mul_f32 v[226:227], v[226:227], v[86:87] op_sel_hi:[1,0]
	v_pk_mul_f32 v[228:229], v[228:229], v[86:87] op_sel_hi:[1,0]
	v_pk_fma_f32 v[214:215], v[0:1], v[214:215], v[8:9]
	v_pk_fma_f32 v[216:217], v[2:3], v[216:217], v[10:11]
	v_pk_fma_f32 v[218:219], v[4:5], v[218:219], v[12:13]
	v_pk_fma_f32 v[220:221], v[6:7], v[220:221], v[14:15]
	v_pk_fma_f32 v[222:223], v[60:61], v[222:223], v[68:69]
	v_pk_fma_f32 v[224:225], v[62:63], v[224:225], v[70:71]
	v_pk_fma_f32 v[226:227], v[64:65], v[226:227], v[72:73]
	v_pk_fma_f32 v[228:229], v[66:67], v[228:229], v[74:75]
	v_cvt_pk_bf16_f32 v214, v214, v215
	v_cvt_pk_bf16_f32 v215, v216, v217
	v_cvt_pk_bf16_f32 v216, v218, v219
	v_cvt_pk_bf16_f32 v217, v220, v221
	v_cvt_pk_bf16_f32 v218, v222, v223
	v_cvt_pk_bf16_f32 v219, v224, v225
	v_cvt_pk_bf16_f32 v220, v226, v227
	v_cvt_pk_bf16_f32 v221, v228, v229
	global_store_dwordx4 v92, v[158:161], s[94:95] offset:0
	global_store_dwordx4 v92, v[162:165], s[94:95] offset:1024
	global_store_dwordx4 v92, v[174:177], s[94:95] offset:2048
	global_store_dwordx4 v92, v[178:181], s[94:95] offset:3072
	s_add_u32 s94, s94, 0x1000
	s_addc_u32 s95, s95, 0
	global_store_dwordx4 v92, v[198:201], s[94:95] offset:0
	global_store_dwordx4 v92, v[202:205], s[94:95] offset:1024
	global_store_dwordx4 v92, v[214:217], s[94:95] offset:2048
	global_store_dwordx4 v92, v[218:221], s[94:95] offset:3072
	s_add_u32 s94, s94, 0x1000
	s_addc_u32 s95, s95, 0
	global_load_dwordx4 v[158:161], v34, s[92:93]
	global_load_dwordx4 v[162:165], v34, s[92:93] offset:16
	global_load_dwordx4 v[166:169], v34, s[92:93] offset:2048
	global_load_dwordx4 v[170:173], v34, s[92:93] offset:2064
	s_add_u32 s92, s92, 0x1000
	s_addc_u32 s93, s93, 0
	global_load_dwordx4 v[174:177], v34, s[92:93]
	global_load_dwordx4 v[178:181], v34, s[92:93] offset:16
	global_load_dwordx4 v[182:185], v34, s[92:93] offset:2048
	global_load_dwordx4 v[186:189], v34, s[92:93] offset:2064
	s_add_u32 s92, s92, 0x1000
	s_addc_u32 s93, s93, 0
	global_load_dwordx4 v[198:201], v34, s[92:93]
	global_load_dwordx4 v[202:205], v34, s[92:93] offset:16
	global_load_dwordx4 v[206:209], v34, s[92:93] offset:2048
	global_load_dwordx4 v[210:213], v34, s[92:93] offset:2064
	s_add_u32 s92, s92, 0x1000
	s_addc_u32 s93, s93, 0
	global_load_dwordx4 v[214:217], v34, s[92:93]
	global_load_dwordx4 v[218:221], v34, s[92:93] offset:16
	global_load_dwordx4 v[222:225], v34, s[92:93] offset:2048
	global_load_dwordx4 v[226:229], v34, s[92:93] offset:2064
	s_add_u32 s92, s92, 0x1000
	s_addc_u32 s93, s93, 0
	s_waitcnt vmcnt(24)
	v_mul_f32_e32 v48, v95, v95
	v_mul_f32_e32 v49, v99, v99
	v_mul_f32_e32 v50, v103, v103
	v_mul_f32_e32 v51, v107, v107
	v_fma_f32 v48, v94, v94, v48
	v_fma_f32 v49, v98, v98, v49
	v_fma_f32 v50, v102, v102, v50
	v_fma_f32 v51, v106, v106, v51
	v_fma_f32 v48, v96, v96, v48
	v_fma_f32 v49, v100, v100, v49
	v_fma_f32 v50, v104, v104, v50
	v_fma_f32 v51, v108, v108, v51
	v_fma_f32 v48, v97, v97, v48
	v_fma_f32 v49, v101, v101, v49
	v_fma_f32 v50, v105, v105, v50
	v_fma_f32 v51, v109, v109, v51
	v_add_f32_e32 v44, v48, v49
	v_add_f32_e32 v44, v44, v50
	v_add_f32_e32 v44, v44, v51
	v_mul_f32_e32 v56, v111, v111
	v_mul_f32_e32 v57, v115, v115
	v_mul_f32_e32 v58, v119, v119
	v_mul_f32_e32 v59, v123, v123
	v_fma_f32 v56, v110, v110, v56
	v_fma_f32 v57, v114, v114, v57
	v_fma_f32 v58, v118, v118, v58
	v_fma_f32 v59, v122, v122, v59
	v_fma_f32 v56, v112, v112, v56
	v_fma_f32 v57, v116, v116, v57
	v_fma_f32 v58, v120, v120, v58
	v_fma_f32 v59, v124, v124, v59
	v_fma_f32 v56, v113, v113, v56
	v_fma_f32 v57, v117, v117, v57
	v_fma_f32 v58, v121, v121, v58
	v_fma_f32 v59, v125, v125, v59
	v_add_f32_e32 v52, v56, v57
	v_add_f32_e32 v52, v52, v58
	v_add_f32_e32 v52, v52, v59
	v_mul_f32_e32 v80, v127, v127
	v_mul_f32_e32 v81, v131, v131
	v_mul_f32_e32 v82, v135, v135
	v_mul_f32_e32 v83, v139, v139
	v_fma_f32 v80, v126, v126, v80
	v_fma_f32 v81, v130, v130, v81
	v_fma_f32 v82, v134, v134, v82
	v_fma_f32 v83, v138, v138, v83
	v_fma_f32 v80, v128, v128, v80
	v_fma_f32 v81, v132, v132, v81
	v_fma_f32 v82, v136, v136, v82
	v_fma_f32 v83, v140, v140, v83
	v_fma_f32 v80, v129, v129, v80
	v_fma_f32 v81, v133, v133, v81
	v_fma_f32 v82, v137, v137, v82
	v_fma_f32 v83, v141, v141, v83
	v_add_f32_e32 v76, v80, v81
	v_add_f32_e32 v76, v76, v82
	v_add_f32_e32 v76, v76, v83
	v_mul_f32_e32 v88, v143, v143
	v_mul_f32_e32 v89, v147, v147
	v_mul_f32_e32 v90, v151, v151
	v_mul_f32_e32 v91, v155, v155
	v_fma_f32 v88, v142, v142, v88
	v_fma_f32 v89, v146, v146, v89
	v_fma_f32 v90, v150, v150, v90
	v_fma_f32 v91, v154, v154, v91
	v_fma_f32 v88, v144, v144, v88
	v_fma_f32 v89, v148, v148, v89
	v_fma_f32 v90, v152, v152, v90
	v_fma_f32 v91, v156, v156, v91
	v_fma_f32 v88, v145, v145, v88
	v_fma_f32 v89, v149, v149, v89
	v_fma_f32 v90, v153, v153, v90
	v_fma_f32 v91, v157, v157, v91
	v_add_f32_e32 v84, v88, v89
	v_add_f32_e32 v84, v84, v90
	v_add_f32_e32 v84, v84, v91
	ds_bpermute_b32 v45, v35, v44
	ds_bpermute_b32 v53, v35, v52
	ds_bpermute_b32 v77, v35, v76
	ds_bpermute_b32 v85, v35, v84
	s_waitcnt lgkmcnt(0)
	v_add_f32_e32 v44, v44, v45
	v_add_f32_e32 v52, v52, v53
	v_add_f32_e32 v76, v76, v77
	v_add_f32_e32 v84, v84, v85
	ds_bpermute_b32 v45, v36, v44
	ds_bpermute_b32 v53, v36, v52
	ds_bpermute_b32 v77, v36, v76
	ds_bpermute_b32 v85, v36, v84
	s_waitcnt lgkmcnt(0)
	v_add_f32_e32 v44, v44, v45
	v_add_f32_e32 v52, v52, v53
	v_add_f32_e32 v76, v76, v77
	v_add_f32_e32 v84, v84, v85
	ds_bpermute_b32 v45, v37, v44
	ds_bpermute_b32 v53, v37, v52
	ds_bpermute_b32 v77, v37, v76
	ds_bpermute_b32 v85, v37, v84
	s_waitcnt lgkmcnt(0)
	v_add_f32_e32 v44, v44, v45
	v_add_f32_e32 v52, v52, v53
	v_add_f32_e32 v76, v76, v77
	v_add_f32_e32 v84, v84, v85
	ds_bpermute_b32 v45, v38, v44
	ds_bpermute_b32 v53, v38, v52
	ds_bpermute_b32 v77, v38, v76
	ds_bpermute_b32 v85, v38, v84
	s_waitcnt lgkmcnt(0)
	v_add_f32_e32 v44, v44, v45
	v_add_f32_e32 v52, v52, v53
	v_add_f32_e32 v76, v76, v77
	v_add_f32_e32 v84, v84, v85
	ds_bpermute_b32 v45, v39, v44
	ds_bpermute_b32 v53, v39, v52
	ds_bpermute_b32 v77, v39, v76
	ds_bpermute_b32 v85, v39, v84
	s_waitcnt lgkmcnt(0)
	v_add_f32_e32 v44, v44, v45
	v_add_f32_e32 v52, v52, v53
	v_add_f32_e32 v76, v76, v77
	v_add_f32_e32 v84, v84, v85
	ds_bpermute_b32 v45, v40, v44
	ds_bpermute_b32 v53, v40, v52
	ds_bpermute_b32 v77, v40, v76
	ds_bpermute_b32 v85, v40, v84
	s_waitcnt lgkmcnt(0)
	v_add_f32_e32 v44, v44, v45
	v_add_f32_e32 v52, v52, v53
	v_add_f32_e32 v76, v76, v77
	v_add_f32_e32 v84, v84, v85
	v_fmamk_f32 v44, v44, 0x3a800000, v42
	v_mul_f32_e32 v45, 0x4b800000, v44
	v_cmp_gt_f32_e32 vcc, s46, v44
	s_nop 1
	v_cndmask_b32_e32 v44, v44, v45, vcc
	v_rsq_f32_e32 v44, v44
	s_nop 0
	v_mul_f32_e32 v45, 0x45800000, v44
	v_cndmask_b32_e32 v46, v44, v45, vcc
	v_fmamk_f32 v52, v52, 0x3a800000, v42
	v_mul_f32_e32 v53, 0x4b800000, v52
	v_cmp_gt_f32_e32 vcc, s46, v52
	s_nop 1
	v_cndmask_b32_e32 v52, v52, v53, vcc
	v_rsq_f32_e32 v52, v52
	s_nop 0
	v_mul_f32_e32 v53, 0x45800000, v52
	v_cndmask_b32_e32 v54, v52, v53, vcc
	v_fmamk_f32 v76, v76, 0x3a800000, v42
	v_mul_f32_e32 v77, 0x4b800000, v76
	v_cmp_gt_f32_e32 vcc, s46, v76
	s_nop 1
	v_cndmask_b32_e32 v76, v76, v77, vcc
	v_rsq_f32_e32 v76, v76
	s_nop 0
	v_mul_f32_e32 v77, 0x45800000, v76
	v_cndmask_b32_e32 v78, v76, v77, vcc
	v_fmamk_f32 v84, v84, 0x3a800000, v42
	v_mul_f32_e32 v85, 0x4b800000, v84
	v_cmp_gt_f32_e32 vcc, s46, v84
	s_nop 1
	v_cndmask_b32_e32 v84, v84, v85, vcc
	v_rsq_f32_e32 v84, v84
	s_nop 0
	v_mul_f32_e32 v85, 0x45800000, v84
	v_cndmask_b32_e32 v86, v84, v85, vcc
	v_pk_mul_f32 v[94:95], v[94:95], v[46:47] op_sel_hi:[1,0]
	v_pk_mul_f32 v[96:97], v[96:97], v[46:47] op_sel_hi:[1,0]
	v_pk_mul_f32 v[98:99], v[98:99], v[46:47] op_sel_hi:[1,0]
	v_pk_mul_f32 v[100:101], v[100:101], v[46:47] op_sel_hi:[1,0]
	v_pk_mul_f32 v[102:103], v[102:103], v[46:47] op_sel_hi:[1,0]
	v_pk_mul_f32 v[104:105], v[104:105], v[46:47] op_sel_hi:[1,0]
	v_pk_mul_f32 v[106:107], v[106:107], v[46:47] op_sel_hi:[1,0]
	v_pk_mul_f32 v[108:109], v[108:109], v[46:47] op_sel_hi:[1,0]
	v_pk_fma_f32 v[94:95], v[0:1], v[94:95], v[8:9]
	v_pk_fma_f32 v[96:97], v[2:3], v[96:97], v[10:11]
	v_pk_fma_f32 v[98:99], v[4:5], v[98:99], v[12:13]
	v_pk_fma_f32 v[100:101], v[6:7], v[100:101], v[14:15]
	v_pk_fma_f32 v[102:103], v[60:61], v[102:103], v[68:69]
	v_pk_fma_f32 v[104:105], v[62:63], v[104:105], v[70:71]
	v_pk_fma_f32 v[106:107], v[64:65], v[106:107], v[72:73]
	v_pk_fma_f32 v[108:109], v[66:67], v[108:109], v[74:75]
	v_cvt_pk_bf16_f32 v94, v94, v95
	v_cvt_pk_bf16_f32 v95, v96, v97
	v_cvt_pk_bf16_f32 v96, v98, v99
	v_cvt_pk_bf16_f32 v97, v100, v101
	v_cvt_pk_bf16_f32 v98, v102, v103
	v_cvt_pk_bf16_f32 v99, v104, v105
	v_cvt_pk_bf16_f32 v100, v106, v107
	v_cvt_pk_bf16_f32 v101, v108, v109
	v_pk_mul_f32 v[110:111], v[110:111], v[54:55] op_sel_hi:[1,0]
	v_pk_mul_f32 v[112:113], v[112:113], v[54:55] op_sel_hi:[1,0]
	v_pk_mul_f32 v[114:115], v[114:115], v[54:55] op_sel_hi:[1,0]
	v_pk_mul_f32 v[116:117], v[116:117], v[54:55] op_sel_hi:[1,0]
	v_pk_mul_f32 v[118:119], v[118:119], v[54:55] op_sel_hi:[1,0]
	v_pk_mul_f32 v[120:121], v[120:121], v[54:55] op_sel_hi:[1,0]
	v_pk_mul_f32 v[122:123], v[122:123], v[54:55] op_sel_hi:[1,0]
	v_pk_mul_f32 v[124:125], v[124:125], v[54:55] op_sel_hi:[1,0]
	v_pk_fma_f32 v[110:111], v[0:1], v[110:111], v[8:9]
	v_pk_fma_f32 v[112:113], v[2:3], v[112:113], v[10:11]
	v_pk_fma_f32 v[114:115], v[4:5], v[114:115], v[12:13]
	v_pk_fma_f32 v[116:117], v[6:7], v[116:117], v[14:15]
	v_pk_fma_f32 v[118:119], v[60:61], v[118:119], v[68:69]
	v_pk_fma_f32 v[120:121], v[62:63], v[120:121], v[70:71]
	v_pk_fma_f32 v[122:123], v[64:65], v[122:123], v[72:73]
	v_pk_fma_f32 v[124:125], v[66:67], v[124:125], v[74:75]
	v_cvt_pk_bf16_f32 v110, v110, v111
	v_cvt_pk_bf16_f32 v111, v112, v113
	v_cvt_pk_bf16_f32 v112, v114, v115
	v_cvt_pk_bf16_f32 v113, v116, v117
	v_cvt_pk_bf16_f32 v114, v118, v119
	v_cvt_pk_bf16_f32 v115, v120, v121
	v_cvt_pk_bf16_f32 v116, v122, v123
	v_cvt_pk_bf16_f32 v117, v124, v125
	v_pk_mul_f32 v[126:127], v[126:127], v[78:79] op_sel_hi:[1,0]
	v_pk_mul_f32 v[128:129], v[128:129], v[78:79] op_sel_hi:[1,0]
	v_pk_mul_f32 v[130:131], v[130:131], v[78:79] op_sel_hi:[1,0]
	v_pk_mul_f32 v[132:133], v[132:133], v[78:79] op_sel_hi:[1,0]
	v_pk_mul_f32 v[134:135], v[134:135], v[78:79] op_sel_hi:[1,0]
	v_pk_mul_f32 v[136:137], v[136:137], v[78:79] op_sel_hi:[1,0]
	v_pk_mul_f32 v[138:139], v[138:139], v[78:79] op_sel_hi:[1,0]
	v_pk_mul_f32 v[140:141], v[140:141], v[78:79] op_sel_hi:[1,0]
	v_pk_fma_f32 v[126:127], v[0:1], v[126:127], v[8:9]
	v_pk_fma_f32 v[128:129], v[2:3], v[128:129], v[10:11]
	v_pk_fma_f32 v[130:131], v[4:5], v[130:131], v[12:13]
	v_pk_fma_f32 v[132:133], v[6:7], v[132:133], v[14:15]
	v_pk_fma_f32 v[134:135], v[60:61], v[134:135], v[68:69]
	v_pk_fma_f32 v[136:137], v[62:63], v[136:137], v[70:71]
	v_pk_fma_f32 v[138:139], v[64:65], v[138:139], v[72:73]
	v_pk_fma_f32 v[140:141], v[66:67], v[140:141], v[74:75]
	v_cvt_pk_bf16_f32 v126, v126, v127
	v_cvt_pk_bf16_f32 v127, v128, v129
	v_cvt_pk_bf16_f32 v128, v130, v131
	v_cvt_pk_bf16_f32 v129, v132, v133
	v_cvt_pk_bf16_f32 v130, v134, v135
	v_cvt_pk_bf16_f32 v131, v136, v137
	v_cvt_pk_bf16_f32 v132, v138, v139
	v_cvt_pk_bf16_f32 v133, v140, v141
	v_pk_mul_f32 v[142:143], v[142:143], v[86:87] op_sel_hi:[1,0]
	v_pk_mul_f32 v[144:145], v[144:145], v[86:87] op_sel_hi:[1,0]
	v_pk_mul_f32 v[146:147], v[146:147], v[86:87] op_sel_hi:[1,0]
	v_pk_mul_f32 v[148:149], v[148:149], v[86:87] op_sel_hi:[1,0]
	v_pk_mul_f32 v[150:151], v[150:151], v[86:87] op_sel_hi:[1,0]
	v_pk_mul_f32 v[152:153], v[152:153], v[86:87] op_sel_hi:[1,0]
	v_pk_mul_f32 v[154:155], v[154:155], v[86:87] op_sel_hi:[1,0]
	v_pk_mul_f32 v[156:157], v[156:157], v[86:87] op_sel_hi:[1,0]
	v_pk_fma_f32 v[142:143], v[0:1], v[142:143], v[8:9]
	v_pk_fma_f32 v[144:145], v[2:3], v[144:145], v[10:11]
	v_pk_fma_f32 v[146:147], v[4:5], v[146:147], v[12:13]
	v_pk_fma_f32 v[148:149], v[6:7], v[148:149], v[14:15]
	v_pk_fma_f32 v[150:151], v[60:61], v[150:151], v[68:69]
	v_pk_fma_f32 v[152:153], v[62:63], v[152:153], v[70:71]
	v_pk_fma_f32 v[154:155], v[64:65], v[154:155], v[72:73]
	v_pk_fma_f32 v[156:157], v[66:67], v[156:157], v[74:75]
	v_cvt_pk_bf16_f32 v142, v142, v143
	v_cvt_pk_bf16_f32 v143, v144, v145
	v_cvt_pk_bf16_f32 v144, v146, v147
	v_cvt_pk_bf16_f32 v145, v148, v149
	v_cvt_pk_bf16_f32 v146, v150, v151
	v_cvt_pk_bf16_f32 v147, v152, v153
	v_cvt_pk_bf16_f32 v148, v154, v155
	v_cvt_pk_bf16_f32 v149, v156, v157
	global_store_dwordx4 v92, v[94:97], s[94:95] offset:0
	global_store_dwordx4 v92, v[98:101], s[94:95] offset:1024
	global_store_dwordx4 v92, v[110:113], s[94:95] offset:2048
	global_store_dwordx4 v92, v[114:117], s[94:95] offset:3072
	s_add_u32 s94, s94, 0x1000
	s_addc_u32 s95, s95, 0
	global_store_dwordx4 v92, v[126:129], s[94:95] offset:0
	global_store_dwordx4 v92, v[130:133], s[94:95] offset:1024
	global_store_dwordx4 v92, v[142:145], s[94:95] offset:2048
	global_store_dwordx4 v92, v[146:149], s[94:95] offset:3072
	s_add_u32 s94, s94, 0x1000
	s_addc_u32 s95, s95, 0
	s_sub_u32 s96, s96, 1
	s_cmp_lg_u32 s96, 0
	s_cbranch_scc1 .Ln1_loop
	s_waitcnt vmcnt(8)
	v_mul_f32_e32 v48, v159, v159
	v_mul_f32_e32 v49, v163, v163
	v_mul_f32_e32 v50, v167, v167
	v_mul_f32_e32 v51, v171, v171
	v_fma_f32 v48, v158, v158, v48
	v_fma_f32 v49, v162, v162, v49
	v_fma_f32 v50, v166, v166, v50
	v_fma_f32 v51, v170, v170, v51
	v_fma_f32 v48, v160, v160, v48
	v_fma_f32 v49, v164, v164, v49
	v_fma_f32 v50, v168, v168, v50
	v_fma_f32 v51, v172, v172, v51
	v_fma_f32 v48, v161, v161, v48
	v_fma_f32 v49, v165, v165, v49
	v_fma_f32 v50, v169, v169, v50
	v_fma_f32 v51, v173, v173, v51
	v_add_f32_e32 v44, v48, v49
	v_add_f32_e32 v44, v44, v50
	v_add_f32_e32 v44, v44, v51
	v_mul_f32_e32 v56, v175, v175
	v_mul_f32_e32 v57, v179, v179
	v_mul_f32_e32 v58, v183, v183
	v_mul_f32_e32 v59, v187, v187
	v_fma_f32 v56, v174, v174, v56
	v_fma_f32 v57, v178, v178, v57
	v_fma_f32 v58, v182, v182, v58
	v_fma_f32 v59, v186, v186, v59
	v_fma_f32 v56, v176, v176, v56
	v_fma_f32 v57, v180, v180, v57
	v_fma_f32 v58, v184, v184, v58
	v_fma_f32 v59, v188, v188, v59
	v_fma_f32 v56, v177, v177, v56
	v_fma_f32 v57, v181, v181, v57
	v_fma_f32 v58, v185, v185, v58
	v_fma_f32 v59, v189, v189, v59
	v_add_f32_e32 v52, v56, v57
	v_add_f32_e32 v52, v52, v58
	v_add_f32_e32 v52, v52, v59
	v_mul_f32_e32 v80, v199, v199
	v_mul_f32_e32 v81, v203, v203
	v_mul_f32_e32 v82, v207, v207
	v_mul_f32_e32 v83, v211, v211
	v_fma_f32 v80, v198, v198, v80
	v_fma_f32 v81, v202, v202, v81
	v_fma_f32 v82, v206, v206, v82
	v_fma_f32 v83, v210, v210, v83
	v_fma_f32 v80, v200, v200, v80
	v_fma_f32 v81, v204, v204, v81
	v_fma_f32 v82, v208, v208, v82
	v_fma_f32 v83, v212, v212, v83
	v_fma_f32 v80, v201, v201, v80
	v_fma_f32 v81, v205, v205, v81
	v_fma_f32 v82, v209, v209, v82
	v_fma_f32 v83, v213, v213, v83
	v_add_f32_e32 v76, v80, v81
	v_add_f32_e32 v76, v76, v82
	v_add_f32_e32 v76, v76, v83
	v_mul_f32_e32 v88, v215, v215
	v_mul_f32_e32 v89, v219, v219
	v_mul_f32_e32 v90, v223, v223
	v_mul_f32_e32 v91, v227, v227
	v_fma_f32 v88, v214, v214, v88
	v_fma_f32 v89, v218, v218, v89
	v_fma_f32 v90, v222, v222, v90
	v_fma_f32 v91, v226, v226, v91
	v_fma_f32 v88, v216, v216, v88
	v_fma_f32 v89, v220, v220, v89
	v_fma_f32 v90, v224, v224, v90
	v_fma_f32 v91, v228, v228, v91
	v_fma_f32 v88, v217, v217, v88
	v_fma_f32 v89, v221, v221, v89
	v_fma_f32 v90, v225, v225, v90
	v_fma_f32 v91, v229, v229, v91
	v_add_f32_e32 v84, v88, v89
	v_add_f32_e32 v84, v84, v90
	v_add_f32_e32 v84, v84, v91
	ds_bpermute_b32 v45, v35, v44
	ds_bpermute_b32 v53, v35, v52
	ds_bpermute_b32 v77, v35, v76
	ds_bpermute_b32 v85, v35, v84
	s_waitcnt lgkmcnt(0)
	v_add_f32_e32 v44, v44, v45
	v_add_f32_e32 v52, v52, v53
	v_add_f32_e32 v76, v76, v77
	v_add_f32_e32 v84, v84, v85
	ds_bpermute_b32 v45, v36, v44
	ds_bpermute_b32 v53, v36, v52
	ds_bpermute_b32 v77, v36, v76
	ds_bpermute_b32 v85, v36, v84
	s_waitcnt lgkmcnt(0)
	v_add_f32_e32 v44, v44, v45
	v_add_f32_e32 v52, v52, v53
	v_add_f32_e32 v76, v76, v77
	v_add_f32_e32 v84, v84, v85
	ds_bpermute_b32 v45, v37, v44
	ds_bpermute_b32 v53, v37, v52
	ds_bpermute_b32 v77, v37, v76
	ds_bpermute_b32 v85, v37, v84
	s_waitcnt lgkmcnt(0)
	v_add_f32_e32 v44, v44, v45
	v_add_f32_e32 v52, v52, v53
	v_add_f32_e32 v76, v76, v77
	v_add_f32_e32 v84, v84, v85
	ds_bpermute_b32 v45, v38, v44
	ds_bpermute_b32 v53, v38, v52
	ds_bpermute_b32 v77, v38, v76
	ds_bpermute_b32 v85, v38, v84
	s_waitcnt lgkmcnt(0)
	v_add_f32_e32 v44, v44, v45
	v_add_f32_e32 v52, v52, v53
	v_add_f32_e32 v76, v76, v77
	v_add_f32_e32 v84, v84, v85
	ds_bpermute_b32 v45, v39, v44
	ds_bpermute_b32 v53, v39, v52
	ds_bpermute_b32 v77, v39, v76
	ds_bpermute_b32 v85, v39, v84
	s_waitcnt lgkmcnt(0)
	v_add_f32_e32 v44, v44, v45
	v_add_f32_e32 v52, v52, v53
	v_add_f32_e32 v76, v76, v77
	v_add_f32_e32 v84, v84, v85
	ds_bpermute_b32 v45, v40, v44
	ds_bpermute_b32 v53, v40, v52
	ds_bpermute_b32 v77, v40, v76
	ds_bpermute_b32 v85, v40, v84
	s_waitcnt lgkmcnt(0)
	v_add_f32_e32 v44, v44, v45
	v_add_f32_e32 v52, v52, v53
	v_add_f32_e32 v76, v76, v77
	v_add_f32_e32 v84, v84, v85
	v_fmamk_f32 v44, v44, 0x3a800000, v42
	v_mul_f32_e32 v45, 0x4b800000, v44
	v_cmp_gt_f32_e32 vcc, s46, v44
	s_nop 1
	v_cndmask_b32_e32 v44, v44, v45, vcc
	v_rsq_f32_e32 v44, v44
	s_nop 0
	v_mul_f32_e32 v45, 0x45800000, v44
	v_cndmask_b32_e32 v46, v44, v45, vcc
	v_fmamk_f32 v52, v52, 0x3a800000, v42
	v_mul_f32_e32 v53, 0x4b800000, v52
	v_cmp_gt_f32_e32 vcc, s46, v52
	s_nop 1
	v_cndmask_b32_e32 v52, v52, v53, vcc
	v_rsq_f32_e32 v52, v52
	s_nop 0
	v_mul_f32_e32 v53, 0x45800000, v52
	v_cndmask_b32_e32 v54, v52, v53, vcc
	v_fmamk_f32 v76, v76, 0x3a800000, v42
	v_mul_f32_e32 v77, 0x4b800000, v76
	v_cmp_gt_f32_e32 vcc, s46, v76
	s_nop 1
	v_cndmask_b32_e32 v76, v76, v77, vcc
	v_rsq_f32_e32 v76, v76
	s_nop 0
	v_mul_f32_e32 v77, 0x45800000, v76
	v_cndmask_b32_e32 v78, v76, v77, vcc
	v_fmamk_f32 v84, v84, 0x3a800000, v42
	v_mul_f32_e32 v85, 0x4b800000, v84
	v_cmp_gt_f32_e32 vcc, s46, v84
	s_nop 1
	v_cndmask_b32_e32 v84, v84, v85, vcc
	v_rsq_f32_e32 v84, v84
	s_nop 0
	v_mul_f32_e32 v85, 0x45800000, v84
	v_cndmask_b32_e32 v86, v84, v85, vcc
	v_pk_mul_f32 v[158:159], v[158:159], v[46:47] op_sel_hi:[1,0]
	v_pk_mul_f32 v[160:161], v[160:161], v[46:47] op_sel_hi:[1,0]
	v_pk_mul_f32 v[162:163], v[162:163], v[46:47] op_sel_hi:[1,0]
	v_pk_mul_f32 v[164:165], v[164:165], v[46:47] op_sel_hi:[1,0]
	v_pk_mul_f32 v[166:167], v[166:167], v[46:47] op_sel_hi:[1,0]
	v_pk_mul_f32 v[168:169], v[168:169], v[46:47] op_sel_hi:[1,0]
	v_pk_mul_f32 v[170:171], v[170:171], v[46:47] op_sel_hi:[1,0]
	v_pk_mul_f32 v[172:173], v[172:173], v[46:47] op_sel_hi:[1,0]
	v_pk_fma_f32 v[158:159], v[0:1], v[158:159], v[8:9]
	v_pk_fma_f32 v[160:161], v[2:3], v[160:161], v[10:11]
	v_pk_fma_f32 v[162:163], v[4:5], v[162:163], v[12:13]
	v_pk_fma_f32 v[164:165], v[6:7], v[164:165], v[14:15]
	v_pk_fma_f32 v[166:167], v[60:61], v[166:167], v[68:69]
	v_pk_fma_f32 v[168:169], v[62:63], v[168:169], v[70:71]
	v_pk_fma_f32 v[170:171], v[64:65], v[170:171], v[72:73]
	v_pk_fma_f32 v[172:173], v[66:67], v[172:173], v[74:75]
	v_cvt_pk_bf16_f32 v158, v158, v159
	v_cvt_pk_bf16_f32 v159, v160, v161
	v_cvt_pk_bf16_f32 v160, v162, v163
	v_cvt_pk_bf16_f32 v161, v164, v165
	v_cvt_pk_bf16_f32 v162, v166, v167
	v_cvt_pk_bf16_f32 v163, v168, v169
	v_cvt_pk_bf16_f32 v164, v170, v171
	v_cvt_pk_bf16_f32 v165, v172, v173
	v_pk_mul_f32 v[174:175], v[174:175], v[54:55] op_sel_hi:[1,0]
	v_pk_mul_f32 v[176:177], v[176:177], v[54:55] op_sel_hi:[1,0]
	v_pk_mul_f32 v[178:179], v[178:179], v[54:55] op_sel_hi:[1,0]
	v_pk_mul_f32 v[180:181], v[180:181], v[54:55] op_sel_hi:[1,0]
	v_pk_mul_f32 v[182:183], v[182:183], v[54:55] op_sel_hi:[1,0]
	v_pk_mul_f32 v[184:185], v[184:185], v[54:55] op_sel_hi:[1,0]
	v_pk_mul_f32 v[186:187], v[186:187], v[54:55] op_sel_hi:[1,0]
	v_pk_mul_f32 v[188:189], v[188:189], v[54:55] op_sel_hi:[1,0]
	v_pk_fma_f32 v[174:175], v[0:1], v[174:175], v[8:9]
	v_pk_fma_f32 v[176:177], v[2:3], v[176:177], v[10:11]
	v_pk_fma_f32 v[178:179], v[4:5], v[178:179], v[12:13]
	v_pk_fma_f32 v[180:181], v[6:7], v[180:181], v[14:15]
	v_pk_fma_f32 v[182:183], v[60:61], v[182:183], v[68:69]
	v_pk_fma_f32 v[184:185], v[62:63], v[184:185], v[70:71]
	v_pk_fma_f32 v[186:187], v[64:65], v[186:187], v[72:73]
	v_pk_fma_f32 v[188:189], v[66:67], v[188:189], v[74:75]
	v_cvt_pk_bf16_f32 v174, v174, v175
	v_cvt_pk_bf16_f32 v175, v176, v177
	v_cvt_pk_bf16_f32 v176, v178, v179
	v_cvt_pk_bf16_f32 v177, v180, v181
	v_cvt_pk_bf16_f32 v178, v182, v183
	v_cvt_pk_bf16_f32 v179, v184, v185
	v_cvt_pk_bf16_f32 v180, v186, v187
	v_cvt_pk_bf16_f32 v181, v188, v189
	v_pk_mul_f32 v[198:199], v[198:199], v[78:79] op_sel_hi:[1,0]
	v_pk_mul_f32 v[200:201], v[200:201], v[78:79] op_sel_hi:[1,0]
	v_pk_mul_f32 v[202:203], v[202:203], v[78:79] op_sel_hi:[1,0]
	v_pk_mul_f32 v[204:205], v[204:205], v[78:79] op_sel_hi:[1,0]
	v_pk_mul_f32 v[206:207], v[206:207], v[78:79] op_sel_hi:[1,0]
	v_pk_mul_f32 v[208:209], v[208:209], v[78:79] op_sel_hi:[1,0]
	v_pk_mul_f32 v[210:211], v[210:211], v[78:79] op_sel_hi:[1,0]
	v_pk_mul_f32 v[212:213], v[212:213], v[78:79] op_sel_hi:[1,0]
	v_pk_fma_f32 v[198:199], v[0:1], v[198:199], v[8:9]
	v_pk_fma_f32 v[200:201], v[2:3], v[200:201], v[10:11]
	v_pk_fma_f32 v[202:203], v[4:5], v[202:203], v[12:13]
	v_pk_fma_f32 v[204:205], v[6:7], v[204:205], v[14:15]
	v_pk_fma_f32 v[206:207], v[60:61], v[206:207], v[68:69]
	v_pk_fma_f32 v[208:209], v[62:63], v[208:209], v[70:71]
	v_pk_fma_f32 v[210:211], v[64:65], v[210:211], v[72:73]
	v_pk_fma_f32 v[212:213], v[66:67], v[212:213], v[74:75]
	v_cvt_pk_bf16_f32 v198, v198, v199
	v_cvt_pk_bf16_f32 v199, v200, v201
	v_cvt_pk_bf16_f32 v200, v202, v203
	v_cvt_pk_bf16_f32 v201, v204, v205
	v_cvt_pk_bf16_f32 v202, v206, v207
	v_cvt_pk_bf16_f32 v203, v208, v209
	v_cvt_pk_bf16_f32 v204, v210, v211
	v_cvt_pk_bf16_f32 v205, v212, v213
	v_pk_mul_f32 v[214:215], v[214:215], v[86:87] op_sel_hi:[1,0]
	v_pk_mul_f32 v[216:217], v[216:217], v[86:87] op_sel_hi:[1,0]
	v_pk_mul_f32 v[218:219], v[218:219], v[86:87] op_sel_hi:[1,0]
	v_pk_mul_f32 v[220:221], v[220:221], v[86:87] op_sel_hi:[1,0]
	v_pk_mul_f32 v[222:223], v[222:223], v[86:87] op_sel_hi:[1,0]
	v_pk_mul_f32 v[224:225], v[224:225], v[86:87] op_sel_hi:[1,0]
	v_pk_mul_f32 v[226:227], v[226:227], v[86:87] op_sel_hi:[1,0]
	v_pk_mul_f32 v[228:229], v[228:229], v[86:87] op_sel_hi:[1,0]
	v_pk_fma_f32 v[214:215], v[0:1], v[214:215], v[8:9]
	v_pk_fma_f32 v[216:217], v[2:3], v[216:217], v[10:11]
	v_pk_fma_f32 v[218:219], v[4:5], v[218:219], v[12:13]
	v_pk_fma_f32 v[220:221], v[6:7], v[220:221], v[14:15]
	v_pk_fma_f32 v[222:223], v[60:61], v[222:223], v[68:69]
	v_pk_fma_f32 v[224:225], v[62:63], v[224:225], v[70:71]
	v_pk_fma_f32 v[226:227], v[64:65], v[226:227], v[72:73]
	v_pk_fma_f32 v[228:229], v[66:67], v[228:229], v[74:75]
	v_cvt_pk_bf16_f32 v214, v214, v215
	v_cvt_pk_bf16_f32 v215, v216, v217
	v_cvt_pk_bf16_f32 v216, v218, v219
	v_cvt_pk_bf16_f32 v217, v220, v221
	v_cvt_pk_bf16_f32 v218, v222, v223
	v_cvt_pk_bf16_f32 v219, v224, v225
	v_cvt_pk_bf16_f32 v220, v226, v227
	v_cvt_pk_bf16_f32 v221, v228, v229
	global_store_dwordx4 v92, v[158:161], s[94:95] offset:0
	global_store_dwordx4 v92, v[162:165], s[94:95] offset:1024
	global_store_dwordx4 v92, v[174:177], s[94:95] offset:2048
	global_store_dwordx4 v92, v[178:181], s[94:95] offset:3072
	s_add_u32 s94, s94, 0x1000
	s_addc_u32 s95, s95, 0
	global_store_dwordx4 v92, v[198:201], s[94:95] offset:0
	global_store_dwordx4 v92, v[202:205], s[94:95] offset:1024
	global_store_dwordx4 v92, v[214:217], s[94:95] offset:2048
	global_store_dwordx4 v92, v[218:221], s[94:95] offset:3072
	s_add_u32 s94, s94, 0x1000
	s_addc_u32 s95, s95, 0
	s_ashr_i32 s25, s24, 31
	v_lshl_add_u64 v[32:33], s[24:25], 3, v[16:17]
	v_lshlrev_b64 v[0:1], 12, v[32:33]
	v_lshl_add_u64 v[44:45], v[20:21], 0, v[0:1]
	flat_load_dwordx4 v[0:3], v[44:45]
	flat_load_dwordx4 v[4:7], v[44:45] offset:16
	flat_load_dwordx4 v[8:11], v[44:45] offset:2048
	flat_load_dwordx4 v[12:15], v[44:45] offset:2064
	v_lshlrev_b64 v[32:33], 11, v[32:33]
	v_lshl_add_u64 v[32:33], s[12:13], 0, v[32:33]
	v_lshl_add_u64 v[32:33], v[32:33], 0, s[22:23]
	s_add_i32 s24, s24, s38
	v_lshl_add_u64 v[24:25], v[24:25], 0, s[16:17]
	s_cmpk_gt_i32 s24, 0xff
	v_lshl_add_u64 v[26:27], v[26:27], 0, s[18:19]
	s_waitcnt vmcnt(0) lgkmcnt(0)
	v_mov_b32_e32 v46, v1
	v_mov_b32_e32 v47, v5
	v_mov_b32_e32 v44, v0
	v_mov_b32_e32 v45, v4
	v_mov_b32_e32 v54, v9
	v_mov_b32_e32 v55, v13
	v_pk_mul_f32 v[46:47], v[46:47], v[46:47]
	v_mov_b32_e32 v48, v2
	v_mov_b32_e32 v49, v6
	v_mov_b32_e32 v52, v8
	v_mov_b32_e32 v53, v12
	v_pk_mul_f32 v[54:55], v[54:55], v[54:55]
	v_pk_fma_f32 v[44:45], v[44:45], v[44:45], v[46:47]
	v_mov_b32_e32 v50, v3
	v_mov_b32_e32 v51, v7
	v_mov_b32_e32 v56, v10
	v_mov_b32_e32 v57, v14
	v_pk_fma_f32 v[46:47], v[52:53], v[52:53], v[54:55]
	v_pk_fma_f32 v[44:45], v[48:49], v[48:49], v[44:45]
	v_mov_b32_e32 v58, v11
	v_mov_b32_e32 v59, v15
	v_pk_fma_f32 v[46:47], v[56:57], v[56:57], v[46:47]
	v_pk_fma_f32 v[44:45], v[50:51], v[50:51], v[44:45]
	v_pk_fma_f32 v[46:47], v[58:59], v[58:59], v[46:47]
	v_add_f32_e32 v18, v44, v45
	v_add_f32_e32 v18, v18, v46
	v_add_f32_e32 v18, v18, v47
	ds_bpermute_b32 v29, v35, v18
	ds_read_b128 v[44:47], v34 offset:8192
	ds_read_b128 v[48:51], v34 offset:8208
	ds_read_b128 v[52:55], v34 offset:12288
	ds_read_b128 v[56:59], v34 offset:12304
	ds_read_b128 v[60:63], v34 offset:10240
	ds_read_b128 v[64:67], v34 offset:10256
	ds_read_b128 v[68:71], v34 offset:14336
	ds_read_b128 v[72:75], v34 offset:14352
	s_waitcnt lgkmcnt(8)
	v_add_f32_e32 v18, v18, v29
	ds_bpermute_b32 v29, v36, v18
	s_waitcnt lgkmcnt(0)
	v_add_f32_e32 v18, v18, v29
	ds_bpermute_b32 v29, v37, v18
	s_waitcnt lgkmcnt(0)
	v_add_f32_e32 v18, v18, v29
	ds_bpermute_b32 v31, v38, v18
	v_mov_b32_e32 v29, v19
	v_lshl_add_u64 v[76:77], v[32:33], 0, v[28:29]
	s_waitcnt lgkmcnt(0)
	v_add_f32_e32 v18, v18, v31
	ds_bpermute_b32 v43, v39, v18
	v_mov_b32_e32 v31, v19
	v_lshl_add_u64 v[32:33], v[32:33], 0, v[30:31]
	s_waitcnt lgkmcnt(0)
	v_add_f32_e32 v18, v18, v43
	ds_bpermute_b32 v43, v40, v18
	s_waitcnt lgkmcnt(0)
	v_add_f32_e32 v18, v18, v43
	v_fmamk_f32 v18, v18, 0x3a800000, v42
	v_mul_f32_e32 v43, 0x4b800000, v18
	v_cmp_gt_f32_e32 vcc, s46, v18
	s_nop 1
	v_cndmask_b32_e32 v18, v18, v43, vcc
	v_rsq_f32_e32 v18, v18
	s_nop 0
	v_mul_f32_e32 v29, 0x45800000, v18
	v_cndmask_b32_e32 v18, v18, v29, vcc
	v_pk_mul_f32 v[0:1], v[0:1], v[18:19] op_sel_hi:[1,0]
	v_pk_mul_f32 v[2:3], v[2:3], v[18:19] op_sel_hi:[1,0]
	v_pk_mul_f32 v[4:5], v[4:5], v[18:19] op_sel_hi:[1,0]
	v_pk_mul_f32 v[6:7], v[6:7], v[18:19] op_sel_hi:[1,0]
	v_pk_fma_f32 v[2:3], v[46:47], v[2:3], v[54:55]
	v_pk_fma_f32 v[0:1], v[44:45], v[0:1], v[52:53]
	v_pk_mul_f32 v[8:9], v[8:9], v[18:19] op_sel_hi:[1,0]
	v_pk_mul_f32 v[10:11], v[10:11], v[18:19] op_sel_hi:[1,0]
	v_pk_mul_f32 v[12:13], v[12:13], v[18:19] op_sel_hi:[1,0]
	v_pk_mul_f32 v[14:15], v[14:15], v[18:19] op_sel_hi:[1,0]
	v_pk_fma_f32 v[6:7], v[50:51], v[6:7], v[58:59]
	v_pk_fma_f32 v[4:5], v[48:49], v[4:5], v[56:57]
	v_cvt_pk_bf16_f32 v0, v0, v1
	v_cvt_pk_bf16_f32 v1, v2, v3
	v_cvt_pk_bf16_f32 v3, v6, v7
	v_pk_fma_f32 v[10:11], v[62:63], v[10:11], v[70:71]
	v_cvt_pk_bf16_f32 v2, v4, v5
	v_pk_fma_f32 v[8:9], v[60:61], v[8:9], v[68:69]
	v_pk_fma_f32 v[14:15], v[66:67], v[14:15], v[74:75]
	v_pk_fma_f32 v[12:13], v[64:65], v[12:13], v[72:73]
	v_cvt_pk_bf16_f32 v4, v8, v9
	v_cvt_pk_bf16_f32 v5, v10, v11
	v_cvt_pk_bf16_f32 v7, v14, v15
	s_nop 0
	v_cvt_pk_bf16_f32 v6, v12, v13
	flat_store_dwordx4 v[76:77], v[0:3]
	flat_store_dwordx4 v[32:33], v[4:7]
	s_cbranch_scc0 .LBB0_61
